# weight-transpose loop: loop-top vmcnt(0) relaxed to a counted wait so the previous pair's stores drain under the next pair's loads
# baseline (speedup 1.0000x reference)
.LBB0_89:
	v_add_u32_e32 v14, s20, v32
	s_movk_i32 s0, 0x45ff
	v_subrev_u32_e32 v3, s15, v1
	v_cmp_lt_i32_e32 vcc, s0, v14
	v_mov_b64_e32 v[6:7], 0
	v_mov_b64_e32 v[4:5], 0x800
	s_waitcnt vmcnt(8)
	v_mov_b32_e32 v23, 0x4600
	v_mov_b64_e32 v[16:17], s[42:43]
	v_mov_b64_e32 v[10:11], s[44:45]
	v_mov_b32_e32 v25, 0x4600
	v_mov_b64_e32 v[8:9], 0x800
	v_mov_b64_e32 v[12:13], 0
	s_and_saveexec_b64 s[0:1], vcc
	s_cbranch_execz .LBB0_103
	s_movk_i32 s22, 0x49ff
	v_cmp_lt_u32_e32 vcc, s22, v14
	s_and_saveexec_b64 s[22:23], vcc
	s_xor_b64 s[48:49], exec, s[22:23]
	s_cbranch_execz .LBB0_100
	s_movk_i32 s22, 0x4dff
	v_cmp_lt_u32_e32 vcc, s22, v14
	s_and_saveexec_b64 s[22:23], vcc
	s_xor_b64 s[50:51], exec, s[22:23]
	s_cbranch_execz .LBB0_97
	s_movk_i32 s22, 0x4fff
	v_cmp_lt_u32_e32 vcc, s22, v14
	s_and_saveexec_b64 s[22:23], vcc
	s_xor_b64 s[52:53], exec, s[22:23]
	v_add_u32_e32 v3, 0xffffb000, v14
	s_or_saveexec_b64 s[52:53], s[52:53]
	v_mov_b64_e32 v[8:9], 0x800
	v_mov_b64_e32 v[12:13], 0
	v_mov_b64_e32 v[10:11], s[10:11]
	v_mov_b64_e32 v[16:17], s[8:9]
	s_xor_b64 exec, exec, s[52:53]
	v_add_u32_e32 v3, 0xffffb200, v3
	v_mov_b64_e32 v[8:9], 0xa00
	v_mov_b64_e32 v[12:13], 0x800
	v_mov_b64_e32 v[10:11], s[36:37]
	v_mov_b64_e32 v[16:17], s[30:31]
	s_or_b64 exec, exec, s[52:53]
